# attention on even blockIdx%8 (XCDs), scan on odd: interleaved instead of halves
# speedup vs baseline: 1.0472x; 1.0036x over previous
; __device__ __forceinline__ int bid_() { int b = blockIdx.x; asm volatile("" : "+s"(b)); return b; }
; __device__ __forceinline__ void phase_scan(CParams& P, LAS unsigned char* lds) {
;     ...
;     const int bx_ = bid_(); const int vcu_ = (nb_ % 8 == 0) ? (bx_ % 8) * (nb_ / 8) + bx_ / 8 : bx_;
;     for (int task = vcu_; task < GSEQ * 8 * 2 * 2; task += nb_) {
;         const int rowhalf = task & 1, dir = (task >> 1) & 1, h = (task >> 2) & 7, s = task >> 5;
;         float* OUT = (float*)(P.ws + WS_P2) + (size_t)dir * TG * 512;
;         __syncthreads();
;         if (wid >= 4) {
;             const int ltid = tid - 256; f16x8 v[6];
;     ...
;             SC_GLOAD(0); SC_WRITE(0); SC_GLOAD(1);
; #pragma unroll 1
;             for (int c = 0; c < NCH; ++c) {
;                 __syncthreads();
;                 if (c + 1 < NCH) { SC_WRITE(c + 1); if (c + 2 < NCH) SC_GLOAD(c + 2); }
;             }
;             __syncthreads();
;     ...
;         } else {
;             const int rl = lane >> 3, oct = lane & 7, rloc = wid * 8 + rl;
;             __builtin_amdgcn_s_setprio(3);
;             f32x4 s0 = {0.f, 0.f, 0.f, 0.f}, s1 = {0.f, 0.f, 0.f, 0.f};
;             float* op = OUT + ((size_t)s * SEQ + (dir ? SEQ - 1 : 0)) * 512 + h * 64 + rowhalf * 32 + rloc; const long ostep = dir ? -512 : 512;
.Lr3_scan:
	s_waitcnt vmcnt(0)
	s_bfe_u32 s4, s2, 0x20001
	s_lshl_b32 s4, s4, 5
	s_lshr_b32 s5, s2, 3
	s_add_i32 s4, s4, s5
	s_lshr_b32 s7, s4, 4
	s_and_b32 s5, s4, 1
	s_bfe_u32 s6, s4, 0x30001
	s_mul_i32 s9, s7, 0xc00000
	s_mul_i32 s12, s6, 0x180
	s_add_i32 s9, s9, s12
	s_add_i32 s12, s9, 0x1a000000
	s_add_u32 s40, s22, s12
	s_addc_u32 s41, s23, 0
	s_mul_i32 s12, s5, 0x6000000
	s_add_i32 s12, s12, s9
	s_add_i32 s12, s12, 0x20000000
	s_add_u32 s42, s22, s12
	s_addc_u32 s43, s23, 0
	s_lshl_b32 s12, s7, 22
	s_lshl_b32 s15, s6, 7
	s_add_i32 s12, s12, s15
	s_add_i32 s12, s12, 0x2e000000
	s_add_u32 s44, s22, s12
	s_addc_u32 s45, s23, 0
	s_lshl_b32 s12, s7, 23
	s_lshl_b32 s15, s6, 8
	s_add_i32 s12, s12, s15
	s_lshl_b32 s15, s5, 26
	s_add_i32 s12, s12, s15
	s_add_i32 s12, s12, 0x8000000
	s_add_u32 s10, s22, s12
	s_addc_u32 s11, s23, 0
	s_cmp_eq_u32 s5, 0
	s_cselect_b32 s46, 0, 0xfff
	s_mov_b32 s47, 0xfffe8000
	s_cselect_b32 s48, 0x18000, s47
	s_cselect_b32 s49, 0, -1
	s_mov_b32 s47, 0xffff8000
	s_cselect_b32 s36, 0x8000, s47
	s_cselect_b32 s37, 0, -1
	s_mov_b32 s47, 0xffffe000
	s_cselect_b32 s13, 0x2000, s47
	s_mov_b32 s50, 0xaaaaaaaa
	s_mov_b32 s51, 0xaaaaaaaa
	s_mov_b32 s52, 0xcccccccc
	s_mov_b32 s53, 0xcccccccc
	v_lshrrev_b32_e32 v0, 6, v222
	v_and_b32_e32 v6, 15, v222
	v_readfirstlane_b32 s28, v0
	v_lshrrev_b32_e32 v7, 4, v222
	s_cmp_lt_u32 s28, 4
	s_cselect_b32 s36, s48, s36
	s_cselect_b32 s37, s49, s37
	v_xor_b32_e32 v1, s46, v7
	v_mul_u32_u24_e32 v1, 0xc00, v1
	v_lshlrev_b32_e32 v64, 4, v6
	v_add_u32_e32 v130, v1, v64
	v_mov_b32_e32 v131, 0
	v_and_b32_e32 v1, 8, v6
	v_lshlrev_b32_e32 v1, 4, v1
	v_add_u32_e32 v128, v130, v1
	v_mov_b32_e32 v129, 0
	v_lshl_add_u64 v[152:153], s[40:41], 0, v[128:129]
	v_lshl_add_u64 v[154:155], s[42:43], 0, v[130:131]
	v_mul_u32_u24_e32 v0, 0x500, v7
	v_and_b32_e32 v1, 7, v6
	v_lshlrev_b32_e32 v1, 5, v1
	v_add_u32_e32 v0, v0, v1
	v_and_b32_e32 v1, 8, v6
	v_lshlrev_b32_e32 v127, 7, v1
	v_sub_u32_e32 v127, 0x400, v127
	v_add_u32_e32 v178, v0, v127
	v_lshlrev_b32_e32 v127, 5, v1
	v_add_u32_e32 v127, 0x100, v127
	v_add_u32_e32 v179, v0, v127
	v_lshrrev_b32_e32 v0, 3, v222
	v_and_b32_e32 v0, 31, v0
	v_and_b32_e32 v1, 7, v222
	v_xor_b32_e32 v127, s46, v0
	s_cmp_lt_u32 s28, 4
	s_cbranch_scc0 .Lr3_roleV
	v_mul_u32_u24_e32 v127, 0xc00, v127
	v_lshlrev_b32_e32 v128, 4, v1
	v_add_u32_e32 v128, v127, v128
	v_add_u32_e32 v128, 0x100, v128
	v_mov_b32_e32 v129, 0
	v_lshl_add_u64 v[156:157], s[42:43], 0, v[128:129]
	v_mul_u32_u24_e32 v0, 0x500, v0
	v_lshlrev_b32_e32 v1, 5, v1
	v_add_u32_e32 v0, v0, v1
	v_add_u32_e32 v180, 0x300, v0
	s_branch .Lr3_roleDone

; __device__ __forceinline__ int bid_() { int b = blockIdx.x; asm volatile("" : "+s"(b)); return b; }
; __device__ __forceinline__ int nblk_() { int g = gridDim.x; asm volatile("" : "+s"(g)); return g; }
; __device__ __forceinline__ void phase_attn(CParams& P, LAS unsigned char* lds) {
;     ...
;     const int G = nblk_(), bx = bid_(); const int vcu = (G % 8 == 0) ? (bx % 8) * (G / 8) + bx / 8 : bx;
;     constexpr int KROW = 208, VROW = 272, KBUF = 128 * KROW, VBUF = 64 * VROW, VOFF = 2 * KBUF, NT = SEQ / 128;
;     static_assert(VOFF + 2 * VBUF <= 131072, "attention LDS map");
;     const int kr0 = tid / 12, kc0 = tid % 12, kr1 = (512 + tid) / 12, kc1 = (512 + tid) % 12, kr2 = (1024 + tid) / 12, kc2 = (1024 + tid) % 12, vr0 = tid >> 4, vc0 = tid & 15, vr1 = 32 + vr0, vgo = (vc0 >> 1) * 32 + (vc0 & 1) * 8;
;     ...
;     for (int u = vcu; u < GSEQ * 8 * 16; u += G) {
;         const int sh = u >> 4, qb = u & 15, s = sh >> 3, h = sh & 7; const size_t tok0 = (size_t)s * SEQ;
;         bf16x8 qf[6]; { const bf16_t* qp = Q + (tok0 + qb * 256 + wid * 32 + ql) * 768 + h * 96 + 8 * hi;
; #pragma unroll
;             for (int ds = 0; ds < 6; ++ds) qf[ds] = *(const bf16x8*)(qp + 16 * ds); }
;         const bf16_t* kg0 = KF + (tok0 + kr0) * 768 + h * 96 + kc0 * 8; const bf16_t* kg1 = KF + (tok0 + kr1) * 768 + h * 96 + kc1 * 8; const bf16_t* kg2 = KF + (tok0 + kr2) * 768 + h * 96 + kc2 * 8;
;         const bf16_t* vg0 = VT + ((size_t)(s * 8 + h) * 64 + vr0) * SEQ + vc0 * 8; const bf16_t* vg1 = vg0 + (size_t)32 * SEQ;
.LBB0_606:
	s_and_b64 vcc, exec, s[4:5]
	s_cbranch_vccz .LBB0_627
	s_and_b32 s4, s2, 1
	s_cmp_eq_u32 s4, 1
	s_cbranch_scc1 .Lr3_scan
	s_waitcnt vmcnt(0)
	v_mov_b32_e32 v0, v222
	s_load_dword s10, s[80:81], 0x0
	s_waitcnt lgkmcnt(0)
	s_and_b32 s4, s10, 7
	s_mov_b32 s11, s2
	s_cmp_lg_u32 s4, 0
	s_cbranch_scc1 .LBB0_609
	s_ashr_i32 s5, s11, 31
	s_lshr_b32 s5, s5, 29
	s_add_i32 s5, s11, s5
	s_ashr_i32 s6, s5, 3
	s_and_b32 s5, s5, -8
	s_ashr_i32 s4, s10, 3
	s_sub_i32 s5, s11, s5
	s_mul_i32 s4, s5, s4
	s_add_i32 s11, s4, s6
.LBB0_609:
	s_bfe_u32 s4, s2, 0x20001
	s_lshl_b32 s4, s4, 5
	s_lshr_b32 s11, s2, 3
	s_add_i32 s11, s11, s4
	s_movk_i32 s10, 0x80
	s_cmpk_gt_i32 s11, 0x3ff
	s_cbranch_scc1 .LBB0_626
	v_add_u32_e32 v3, 0x400, v0
	v_mul_hi_i32 v4, v3, s84
	v_lshrrev_b32_e32 v5, 31, v4
	v_ashrrev_i32_e32 v4, 1, v4
	v_add_u32_e32 v158, v4, v5
	v_mul_lo_u32 v4, v158, 12
	v_sub_u32_e32 v10, v3, v4
	v_add_u32_e32 v3, 0x200, v0
	v_mul_hi_i32 v4, v3, s84
	v_lshrrev_b32_e32 v5, 31, v4
	v_ashrrev_i32_e32 v4, 1, v4
	v_add_u32_e32 v160, v4, v5
	v_mul_lo_u32 v4, v160, 12
	v_sub_u32_e32 v11, v3, v4
	v_mul_hi_i32 v3, v0, s84
	v_lshlrev_b32_e32 v2, 3, v0
	v_lshrrev_b32_e32 v4, 31, v3
	v_ashrrev_i32_e32 v3, 1, v3
	v_lshlrev_b32_e32 v1, 4, v0
	v_and_b32_e32 v2, 8, v2
	s_movk_i32 s4, 0xe0
	v_add_u32_e32 v162, v3, v4
	v_and_or_b32 v195, v1, s4, v2
	v_ashrrev_i32_e32 v2, 4, v0
	v_mul_lo_u32 v3, v162, 12
	v_sub_u32_e32 v12, v0, v3
	v_ashrrev_i32_e32 v3, 31, v2
	s_add_u32 s40, s22, 0x34000000
	v_lshlrev_b64 v[4:5], 13, v[2:3]
	v_and_b32_e32 v64, 0xf0, v1
	s_addc_u32 s41, s23, 0
	v_lshl_add_u64 v[6:7], s[22:23], 0, v[4:5]
	s_add_u32 s42, s22, 0x37000000
	v_lshl_add_u64 v[6:7], v[6:7], 0, v[64:65]
	s_mov_b64 s[4:5], 0x3a000000
	s_addc_u32 s43, s23, 0
	v_lshl_add_u64 v[172:173], v[6:7], 0, s[4:5]
	s_movk_i32 s4, 0xd0
	s_add_u32 s44, s22, 0x3c000000
	v_lshlrev_b32_e32 v170, 3, v10
	v_mul_lo_u32 v196, v162, s4
	v_mul_lo_u32 v198, v160, s4
	v_mul_lo_u32 v200, v158, s4
	s_movk_i32 s4, 0x110
	v_or_b32_e32 v4, v4, v64
	s_addc_u32 s45, s23, 0
	v_ashrrev_i32_e32 v171, 31, v170
	v_mul_lo_u32 v202, v2, s4
	v_lshl_add_u64 v[4:5], s[22:23], 0, v[4:5]
	s_mov_b64 s[4:5], 0x3a040100
	v_lshlrev_b32_e32 v168, 3, v11
	v_lshl_add_u64 v[174:175], v[4:5], 0, s[4:5]
	s_add_u32 s4, s22, 0x37030000
	v_lshlrev_b64 v[4:5], 1, v[170:171]
	s_movk_i32 s8, 0x600
	v_ashrrev_i32_e32 v169, 31, v168
	s_addc_u32 s5, s23, 0
	v_mad_i64_i32 v[4:5], s[6:7], v158, s8, v[4:5]
	v_lshlrev_b32_e32 v166, 3, v12
	v_lshl_add_u64 v[176:177], s[4:5], 0, v[4:5]
	v_lshlrev_b64 v[4:5], 1, v[168:169]
	v_and_b32_e32 v1, 31, v0
	v_bfe_u32 v8, v0, 5, 1
	v_ashrrev_i32_e32 v0, 1, v0
	v_ashrrev_i32_e32 v167, 31, v166
	v_mad_i64_i32 v[4:5], s[6:7], v160, s8, v[4:5]
	v_and_b32_e32 v0, 0xffffffe0, v0
	v_lshlrev_b32_e32 v199, 4, v11
	v_lshlrev_b32_e32 v201, 4, v10
	v_mul_u32_u24_e32 v10, 0xd0, v1
	v_lshlrev_b32_e32 v11, 4, v8
	v_lshl_add_u64 v[178:179], s[4:5], 0, v[4:5]
	v_lshlrev_b64 v[4:5], 1, v[166:167]
	v_add_u32_e32 v9, 0, v195
	v_ashrrev_i32_e32 v165, 31, v0
	v_or_b32_e32 v164, v0, v1
	v_lshlrev_b32_e32 v0, 3, v8
	v_add_u32_e32 v3, 0, v196
	v_lshlrev_b32_e32 v197, 4, v12
	v_add_u32_e32 v6, 0, v198
	v_add_u32_e32 v7, 0, v200
	v_lshlrev_b32_e32 v2, 2, v8
	v_add3_u32 v203, 0, v10, v11
	v_mad_i64_i32 v[4:5], s[6:7], v162, s8, v[4:5]
	v_ashrrev_i32_e32 v163, 31, v162
	v_ashrrev_i32_e32 v161, 31, v160
	v_ashrrev_i32_e32 v159, 31, v158
	v_lshl_add_u32 v204, v1, 6, v203
	v_lshl_add_u64 v[180:181], s[4:5], 0, v[4:5]
	v_lshlrev_b32_e32 v64, 1, v0
	v_add_u32_e32 v205, v3, v197
	v_add_u32_e32 v206, v6, v199
	v_add_u32_e32 v207, v7, v201
	v_add_u32_e32 v208, v9, v202
	v_lshlrev_b32_e32 v182, 1, v2
	s_branch .LBB0_612
